# bf16 GEMM epilogue 32-bit store offsets; residual epilogue h loads pipelined through 8 register slots
# baseline (speedup 1.0000x reference)
.LBB0_480:
	s_and_b64 vcc, exec, s[12:13]
	s_cbranch_vccnz .Lres_orig
	v_lshl_add_u32 v152, s23, 8, v154
	v_lshl_or_b32 v153, s22, 8, v163
	v_lshlrev_b32_e32 v152, 12, v152
	v_lshl_add_u32 v144, v153, 2, v152
	v_add_u32_e32 v145, 0x10000, v144
	v_add_u32_e32 v146, 0x20000, v144
	v_add_u32_e32 v147, 0x30000, v144
	v_add_u32_e32 v148, 0x80000, v144
	v_add_u32_e32 v149, 0x90000, v144
	v_add_u32_e32 v150, 0xa0000, v144
	v_add_u32_e32 v151, 0xb0000, v144
	global_load_dwordx4 v[192:195], v144, s[72:73]
	global_load_dwordx4 v[196:199], v144, s[72:73] offset:16
	global_load_dwordx4 v[200:203], v144, s[72:73] offset:512
	global_load_dwordx4 v[204:207], v144, s[72:73] offset:528
	global_load_dwordx4 v[208:211], v145, s[72:73]
	global_load_dwordx4 v[212:215], v145, s[72:73] offset:16
	global_load_dwordx4 v[216:219], v145, s[72:73] offset:512
	global_load_dwordx4 v[220:223], v145, s[72:73] offset:528
	global_load_dwordx4 v[224:227], v146, s[72:73]
	global_load_dwordx4 v[228:231], v146, s[72:73] offset:16
	global_load_dwordx4 v[232:235], v146, s[72:73] offset:512
	global_load_dwordx4 v[236:239], v146, s[72:73] offset:528
	global_load_dwordx4 v[240:243], v147, s[72:73]
	global_load_dwordx4 v[244:247], v147, s[72:73] offset:16
	global_load_dwordx4 v[130:133], v147, s[72:73] offset:512
	global_load_dwordx4 v[176:179], v147, s[72:73] offset:528
	s_waitcnt vmcnt(14)
	v_pk_add_f32 v[126:127], v[126:127], v[192:193]
	v_pk_add_f32 v[128:129], v[128:129], v[194:195]
	v_pk_add_f32 v[122:123], v[122:123], v[196:197]
	v_pk_add_f32 v[124:125], v[124:125], v[198:199]
	global_store_dwordx4 v144, v[126:129], s[72:73]
	global_store_dwordx4 v144, v[122:125], s[72:73] offset:16
	global_load_dwordx4 v[192:195], v148, s[72:73]
	global_load_dwordx4 v[196:199], v148, s[72:73] offset:16
	s_waitcnt vmcnt(16)
	v_pk_add_f32 v[118:119], v[118:119], v[200:201]
	v_pk_add_f32 v[120:121], v[120:121], v[202:203]
	v_pk_add_f32 v[114:115], v[114:115], v[204:205]
	v_pk_add_f32 v[116:117], v[116:117], v[206:207]
	global_store_dwordx4 v144, v[118:121], s[72:73] offset:512
	global_store_dwordx4 v144, v[114:117], s[72:73] offset:528
	global_load_dwordx4 v[200:203], v148, s[72:73] offset:512
	global_load_dwordx4 v[204:207], v148, s[72:73] offset:528
	s_waitcnt vmcnt(18)
	v_pk_add_f32 v[108:109], v[108:109], v[208:209]
	v_pk_add_f32 v[110:111], v[110:111], v[210:211]
	v_pk_add_f32 v[104:105], v[104:105], v[212:213]
	v_pk_add_f32 v[106:107], v[106:107], v[214:215]
	global_store_dwordx4 v145, v[108:111], s[72:73]
	global_store_dwordx4 v145, v[104:107], s[72:73] offset:16
	global_load_dwordx4 v[208:211], v149, s[72:73]
	global_load_dwordx4 v[212:215], v149, s[72:73] offset:16
	s_waitcnt vmcnt(20)
	v_pk_add_f32 v[100:101], v[100:101], v[216:217]
	v_pk_add_f32 v[102:103], v[102:103], v[218:219]
	v_pk_add_f32 v[96:97], v[96:97], v[220:221]
	v_pk_add_f32 v[98:99], v[98:99], v[222:223]
	global_store_dwordx4 v145, v[100:103], s[72:73] offset:512
	global_store_dwordx4 v145, v[96:99], s[72:73] offset:528
	global_load_dwordx4 v[216:219], v149, s[72:73] offset:512
	global_load_dwordx4 v[220:223], v149, s[72:73] offset:528
	s_waitcnt vmcnt(22)
	v_pk_add_f32 v[92:93], v[92:93], v[224:225]
	v_pk_add_f32 v[94:95], v[94:95], v[226:227]
	v_pk_add_f32 v[88:89], v[88:89], v[228:229]
	v_pk_add_f32 v[90:91], v[90:91], v[230:231]
	global_store_dwordx4 v146, v[92:95], s[72:73]
	global_store_dwordx4 v146, v[88:91], s[72:73] offset:16
	global_load_dwordx4 v[224:227], v150, s[72:73]
	global_load_dwordx4 v[228:231], v150, s[72:73] offset:16
	s_waitcnt vmcnt(24)
	v_pk_add_f32 v[84:85], v[84:85], v[232:233]
	v_pk_add_f32 v[86:87], v[86:87], v[234:235]
	v_pk_add_f32 v[80:81], v[80:81], v[236:237]
	v_pk_add_f32 v[82:83], v[82:83], v[238:239]
	global_store_dwordx4 v146, v[84:87], s[72:73] offset:512
	global_store_dwordx4 v146, v[80:83], s[72:73] offset:528
	global_load_dwordx4 v[232:235], v150, s[72:73] offset:512
	global_load_dwordx4 v[236:239], v150, s[72:73] offset:528
	s_waitcnt vmcnt(26)
	v_pk_add_f32 v[76:77], v[76:77], v[240:241]
	v_pk_add_f32 v[78:79], v[78:79], v[242:243]
	v_pk_add_f32 v[72:73], v[72:73], v[244:245]
	v_pk_add_f32 v[74:75], v[74:75], v[246:247]
	global_store_dwordx4 v147, v[76:79], s[72:73]
	global_store_dwordx4 v147, v[72:75], s[72:73] offset:16
	global_load_dwordx4 v[240:243], v151, s[72:73]
	global_load_dwordx4 v[244:247], v151, s[72:73] offset:16
	s_waitcnt vmcnt(28)
	v_pk_add_f32 v[68:69], v[68:69], v[130:131]
	v_pk_add_f32 v[70:71], v[70:71], v[132:133]
	v_pk_add_f32 v[64:65], v[64:65], v[176:177]
	v_pk_add_f32 v[66:67], v[66:67], v[178:179]
	global_store_dwordx4 v147, v[68:71], s[72:73] offset:512
	global_store_dwordx4 v147, v[64:67], s[72:73] offset:528
	global_load_dwordx4 v[130:133], v151, s[72:73] offset:512
	global_load_dwordx4 v[176:179], v151, s[72:73] offset:528
	s_waitcnt vmcnt(28)
	v_pk_add_f32 v[60:61], v[60:61], v[192:193]
	v_pk_add_f32 v[62:63], v[62:63], v[194:195]
	v_pk_add_f32 v[56:57], v[56:57], v[196:197]
	v_pk_add_f32 v[58:59], v[58:59], v[198:199]
	global_store_dwordx4 v148, v[60:63], s[72:73]
	global_store_dwordx4 v148, v[56:59], s[72:73] offset:16
	s_waitcnt vmcnt(26)
	v_pk_add_f32 v[52:53], v[52:53], v[200:201]
	v_pk_add_f32 v[54:55], v[54:55], v[202:203]
	v_pk_add_f32 v[48:49], v[48:49], v[204:205]
	v_pk_add_f32 v[50:51], v[50:51], v[206:207]
	global_store_dwordx4 v148, v[52:55], s[72:73] offset:512
	global_store_dwordx4 v148, v[48:51], s[72:73] offset:528
	s_waitcnt vmcnt(24)
	v_pk_add_f32 v[44:45], v[44:45], v[208:209]
	v_pk_add_f32 v[46:47], v[46:47], v[210:211]
	v_pk_add_f32 v[40:41], v[40:41], v[212:213]
	v_pk_add_f32 v[42:43], v[42:43], v[214:215]
	global_store_dwordx4 v149, v[44:47], s[72:73]
	global_store_dwordx4 v149, v[40:43], s[72:73] offset:16
	s_waitcnt vmcnt(22)
	v_pk_add_f32 v[36:37], v[36:37], v[216:217]
	v_pk_add_f32 v[38:39], v[38:39], v[218:219]
	v_pk_add_f32 v[32:33], v[32:33], v[220:221]
	v_pk_add_f32 v[34:35], v[34:35], v[222:223]
	global_store_dwordx4 v149, v[36:39], s[72:73] offset:512
	global_store_dwordx4 v149, v[32:35], s[72:73] offset:528
	s_waitcnt vmcnt(20)
	v_pk_add_f32 v[28:29], v[28:29], v[224:225]
	v_pk_add_f32 v[30:31], v[30:31], v[226:227]
	v_pk_add_f32 v[24:25], v[24:25], v[228:229]
	v_pk_add_f32 v[26:27], v[26:27], v[230:231]
	global_store_dwordx4 v150, v[28:31], s[72:73]
	global_store_dwordx4 v150, v[24:27], s[72:73] offset:16
	s_waitcnt vmcnt(18)
	v_pk_add_f32 v[20:21], v[20:21], v[232:233]
	v_pk_add_f32 v[22:23], v[22:23], v[234:235]
	v_pk_add_f32 v[16:17], v[16:17], v[236:237]
	v_pk_add_f32 v[18:19], v[18:19], v[238:239]
	global_store_dwordx4 v150, v[20:23], s[72:73] offset:512
	global_store_dwordx4 v150, v[16:19], s[72:73] offset:528
	s_waitcnt vmcnt(16)
	v_pk_add_f32 v[12:13], v[12:13], v[240:241]
	v_pk_add_f32 v[14:15], v[14:15], v[242:243]
	v_pk_add_f32 v[8:9], v[8:9], v[244:245]
	v_pk_add_f32 v[10:11], v[10:11], v[246:247]
	global_store_dwordx4 v151, v[12:15], s[72:73]
	global_store_dwordx4 v151, v[8:11], s[72:73] offset:16
	s_waitcnt vmcnt(14)
	v_pk_add_f32 v[4:5], v[4:5], v[130:131]
	v_pk_add_f32 v[6:7], v[6:7], v[132:133]
	v_pk_add_f32 v[0:1], v[0:1], v[176:177]
	v_pk_add_f32 v[2:3], v[2:3], v[178:179]
	global_store_dwordx4 v151, v[4:7], s[72:73] offset:512
	global_store_dwordx4 v151, v[0:3], s[72:73] offset:528
	s_branch .Lres_join

.Lres_join:
	s_and_b64 vcc, exec, s[36:37]
	s_mov_b64 s[18:19], -1
	s_cbranch_vccnz .LBB0_464
	s_andn2_b64 vcc, exec, s[10:11]
	s_cbranch_vccnz .LBB0_463
	s_barrier
	s_branch .LBB0_463

.LBB0_680:
	v_lshl_add_u32 v112, s53, 8, v146
	v_lshl_or_b32 v114, s52, 8, v148
	v_mad_u32_u24 v144, v112, s6, v114
	v_lshlrev_b32_e32 v144, 1, v144
	v_cvt_pk_bf16_f32 v128, v128, v129
	v_cvt_pk_bf16_f32 v129, v130, v131
	v_cvt_pk_bf16_f32 v130, v124, v125
	v_cvt_pk_bf16_f32 v131, v126, v127
	s_and_b64 vcc, exec, s[38:39]
	global_store_dwordx4 v144, v[128:131], s[24:25]
	s_cbranch_vccnz .LBB0_682
	v_max_f32_e32 v121, 0, v121
	v_max_f32_e32 v120, 0, v120
	v_max_f32_e32 v123, 0, v123
	v_max_f32_e32 v122, 0, v122
	v_max_f32_e32 v117, 0, v117
	v_max_f32_e32 v116, 0, v116
	v_max_f32_e32 v119, 0, v119
	v_max_f32_e32 v118, 0, v118
	v_pk_mul_f32 v[122:123], v[122:123], v[122:123]
	v_pk_mul_f32 v[120:121], v[120:121], v[120:121]
	v_pk_mul_f32 v[118:119], v[118:119], v[118:119]
	v_pk_mul_f32 v[116:117], v[116:117], v[116:117]
.LBB0_682:
	v_cvt_pk_bf16_f32 v120, v120, v121
	v_cvt_pk_bf16_f32 v121, v122, v123
	v_cvt_pk_bf16_f32 v122, v116, v117
	v_cvt_pk_bf16_f32 v123, v118, v119
	s_and_b64 vcc, exec, s[38:39]
	global_store_dwordx4 v144, v[120:123], s[24:25] offset:256
	s_cbranch_vccnz .LBB0_684
	v_max_f32_e32 v109, 0, v109
	v_max_f32_e32 v108, 0, v108
	v_max_f32_e32 v111, 0, v111
	v_max_f32_e32 v110, 0, v110
	v_max_f32_e32 v105, 0, v105
	v_max_f32_e32 v104, 0, v104
	v_max_f32_e32 v107, 0, v107
	v_max_f32_e32 v106, 0, v106
	v_pk_mul_f32 v[110:111], v[110:111], v[110:111]
	v_pk_mul_f32 v[108:109], v[108:109], v[108:109]
	v_pk_mul_f32 v[106:107], v[106:107], v[106:107]
	v_pk_mul_f32 v[104:105], v[104:105], v[104:105]
.LBB0_684:
	s_mul_i32 s20, s6, 32
	v_add_u32_e32 v116, s20, v144
	v_cvt_pk_bf16_f32 v108, v108, v109
	v_cvt_pk_bf16_f32 v109, v110, v111
	v_cvt_pk_bf16_f32 v110, v104, v105
	v_cvt_pk_bf16_f32 v111, v106, v107
	s_and_b64 vcc, exec, s[38:39]
	global_store_dwordx4 v116, v[108:111], s[24:25]
	s_cbranch_vccnz .LBB0_686
	v_max_f32_e32 v101, 0, v101
	v_max_f32_e32 v100, 0, v100
	v_max_f32_e32 v103, 0, v103
	v_max_f32_e32 v102, 0, v102
	v_max_f32_e32 v97, 0, v97
	v_max_f32_e32 v96, 0, v96
	v_max_f32_e32 v99, 0, v99
	v_max_f32_e32 v98, 0, v98
	v_pk_mul_f32 v[102:103], v[102:103], v[102:103]
	v_pk_mul_f32 v[100:101], v[100:101], v[100:101]
	v_pk_mul_f32 v[98:99], v[98:99], v[98:99]
	v_pk_mul_f32 v[96:97], v[96:97], v[96:97]
.LBB0_686:
	v_cvt_pk_bf16_f32 v100, v100, v101
	v_cvt_pk_bf16_f32 v101, v102, v103
	v_cvt_pk_bf16_f32 v102, v96, v97
	v_cvt_pk_bf16_f32 v103, v98, v99
	s_and_b64 vcc, exec, s[38:39]
	global_store_dwordx4 v116, v[100:103], s[24:25] offset:256
	s_cbranch_vccnz .LBB0_688
	v_max_f32_e32 v93, 0, v93
	v_max_f32_e32 v92, 0, v92
	v_max_f32_e32 v95, 0, v95
	v_max_f32_e32 v94, 0, v94
	v_max_f32_e32 v89, 0, v89
	v_max_f32_e32 v88, 0, v88
	v_max_f32_e32 v91, 0, v91
	v_max_f32_e32 v90, 0, v90
	v_pk_mul_f32 v[94:95], v[94:95], v[94:95]
	v_pk_mul_f32 v[92:93], v[92:93], v[92:93]
	v_pk_mul_f32 v[90:91], v[90:91], v[90:91]
	v_pk_mul_f32 v[88:89], v[88:89], v[88:89]
.LBB0_688:
	s_mul_i32 s20, s6, 64
	v_add_u32_e32 v96, s20, v144
	v_cvt_pk_bf16_f32 v92, v92, v93
	v_cvt_pk_bf16_f32 v93, v94, v95
	v_cvt_pk_bf16_f32 v94, v88, v89
	v_cvt_pk_bf16_f32 v95, v90, v91
	s_and_b64 vcc, exec, s[38:39]
	global_store_dwordx4 v96, v[92:95], s[24:25]
	s_cbranch_vccnz .LBB0_690
	v_max_f32_e32 v85, 0, v85
	v_max_f32_e32 v84, 0, v84
	v_max_f32_e32 v87, 0, v87
	v_max_f32_e32 v86, 0, v86
	v_max_f32_e32 v81, 0, v81
	v_max_f32_e32 v80, 0, v80
	v_max_f32_e32 v83, 0, v83
	v_max_f32_e32 v82, 0, v82
	v_pk_mul_f32 v[86:87], v[86:87], v[86:87]
	v_pk_mul_f32 v[84:85], v[84:85], v[84:85]
	v_pk_mul_f32 v[82:83], v[82:83], v[82:83]
	v_pk_mul_f32 v[80:81], v[80:81], v[80:81]
.LBB0_690:
	v_cvt_pk_bf16_f32 v84, v84, v85
	v_cvt_pk_bf16_f32 v85, v86, v87
	v_cvt_pk_bf16_f32 v86, v80, v81
	v_cvt_pk_bf16_f32 v87, v82, v83
	s_and_b64 vcc, exec, s[38:39]
	global_store_dwordx4 v96, v[84:87], s[24:25] offset:256
	s_cbranch_vccnz .LBB0_692
	v_max_f32_e32 v77, 0, v77
	v_max_f32_e32 v76, 0, v76
	v_max_f32_e32 v79, 0, v79
	v_max_f32_e32 v78, 0, v78
	v_max_f32_e32 v73, 0, v73
	v_max_f32_e32 v72, 0, v72
	v_max_f32_e32 v75, 0, v75
	v_max_f32_e32 v74, 0, v74
	v_pk_mul_f32 v[78:79], v[78:79], v[78:79]
	v_pk_mul_f32 v[76:77], v[76:77], v[76:77]
	v_pk_mul_f32 v[74:75], v[74:75], v[74:75]
	v_pk_mul_f32 v[72:73], v[72:73], v[72:73]
.LBB0_692:
	s_mul_i32 s20, s6, 96
	v_add_u32_e32 v80, s20, v144
	v_cvt_pk_bf16_f32 v76, v76, v77
	v_cvt_pk_bf16_f32 v77, v78, v79
	v_cvt_pk_bf16_f32 v78, v72, v73
	v_cvt_pk_bf16_f32 v79, v74, v75
	s_and_b64 vcc, exec, s[38:39]
	global_store_dwordx4 v80, v[76:79], s[24:25]
	s_cbranch_vccnz .LBB0_694
	v_max_f32_e32 v69, 0, v69
	v_max_f32_e32 v68, 0, v68
	v_max_f32_e32 v71, 0, v71
	v_max_f32_e32 v70, 0, v70
	v_max_f32_e32 v65, 0, v65
	v_max_f32_e32 v64, 0, v64
	v_max_f32_e32 v67, 0, v67
	v_max_f32_e32 v66, 0, v66
	v_pk_mul_f32 v[70:71], v[70:71], v[70:71]
	v_pk_mul_f32 v[68:69], v[68:69], v[68:69]
	v_pk_mul_f32 v[66:67], v[66:67], v[66:67]
	v_pk_mul_f32 v[64:65], v[64:65], v[64:65]
.LBB0_694:
	v_cvt_pk_bf16_f32 v68, v68, v69
	v_cvt_pk_bf16_f32 v69, v70, v71
	v_cvt_pk_bf16_f32 v70, v64, v65
	v_cvt_pk_bf16_f32 v71, v66, v67
	s_and_b64 vcc, exec, s[38:39]
	global_store_dwordx4 v80, v[68:71], s[24:25] offset:256
	s_cbranch_vccnz .LBB0_696
	v_max_f32_e32 v61, 0, v61
	v_max_f32_e32 v60, 0, v60
	v_max_f32_e32 v63, 0, v63
	v_max_f32_e32 v62, 0, v62
	v_max_f32_e32 v57, 0, v57
	v_max_f32_e32 v56, 0, v56
	v_max_f32_e32 v59, 0, v59
	v_max_f32_e32 v58, 0, v58
	v_pk_mul_f32 v[62:63], v[62:63], v[62:63]
	v_pk_mul_f32 v[60:61], v[60:61], v[60:61]
	v_pk_mul_f32 v[58:59], v[58:59], v[58:59]
	v_pk_mul_f32 v[56:57], v[56:57], v[56:57]
.LBB0_696:
	s_mul_i32 s20, s6, 256
	v_add_u32_e32 v64, s20, v144
	v_cvt_pk_bf16_f32 v60, v60, v61
	v_cvt_pk_bf16_f32 v61, v62, v63
	v_cvt_pk_bf16_f32 v62, v56, v57
	v_cvt_pk_bf16_f32 v63, v58, v59
	s_and_b64 vcc, exec, s[38:39]
	global_store_dwordx4 v64, v[60:63], s[24:25]
	s_cbranch_vccnz .LBB0_698
	v_max_f32_e32 v53, 0, v53
	v_max_f32_e32 v52, 0, v52
	v_max_f32_e32 v55, 0, v55
	v_max_f32_e32 v54, 0, v54
	v_max_f32_e32 v49, 0, v49
	v_max_f32_e32 v48, 0, v48
	v_max_f32_e32 v51, 0, v51
	v_max_f32_e32 v50, 0, v50
	v_pk_mul_f32 v[54:55], v[54:55], v[54:55]
	v_pk_mul_f32 v[52:53], v[52:53], v[52:53]
	v_pk_mul_f32 v[50:51], v[50:51], v[50:51]
	v_pk_mul_f32 v[48:49], v[48:49], v[48:49]
.LBB0_698:
	v_cvt_pk_bf16_f32 v52, v52, v53
	v_cvt_pk_bf16_f32 v53, v54, v55
	v_cvt_pk_bf16_f32 v54, v48, v49
	v_cvt_pk_bf16_f32 v55, v50, v51
	s_and_b64 vcc, exec, s[38:39]
	global_store_dwordx4 v64, v[52:55], s[24:25] offset:256
	s_cbranch_vccnz .LBB0_700
	v_max_f32_e32 v45, 0, v45
	v_max_f32_e32 v44, 0, v44
	v_max_f32_e32 v47, 0, v47
	v_max_f32_e32 v46, 0, v46
	v_max_f32_e32 v41, 0, v41
	v_max_f32_e32 v40, 0, v40
	v_max_f32_e32 v43, 0, v43
	v_max_f32_e32 v42, 0, v42
	v_pk_mul_f32 v[46:47], v[46:47], v[46:47]
	v_pk_mul_f32 v[44:45], v[44:45], v[44:45]
	v_pk_mul_f32 v[42:43], v[42:43], v[42:43]
	v_pk_mul_f32 v[40:41], v[40:41], v[40:41]
.LBB0_700:
	s_mul_i32 s20, s6, 288
	v_add_u32_e32 v48, s20, v144
	v_cvt_pk_bf16_f32 v44, v44, v45
	v_cvt_pk_bf16_f32 v45, v46, v47
	v_cvt_pk_bf16_f32 v46, v40, v41
	v_cvt_pk_bf16_f32 v47, v42, v43
	s_and_b64 vcc, exec, s[38:39]
	global_store_dwordx4 v48, v[44:47], s[24:25]
	s_cbranch_vccnz .LBB0_702
	v_max_f32_e32 v37, 0, v37
	v_max_f32_e32 v36, 0, v36
	v_max_f32_e32 v39, 0, v39
	v_max_f32_e32 v38, 0, v38
	v_max_f32_e32 v33, 0, v33
	v_max_f32_e32 v32, 0, v32
	v_max_f32_e32 v35, 0, v35
	v_max_f32_e32 v34, 0, v34
	v_pk_mul_f32 v[38:39], v[38:39], v[38:39]
	v_pk_mul_f32 v[36:37], v[36:37], v[36:37]
	v_pk_mul_f32 v[34:35], v[34:35], v[34:35]
	v_pk_mul_f32 v[32:33], v[32:33], v[32:33]
.LBB0_702:
	v_cvt_pk_bf16_f32 v36, v36, v37
	v_cvt_pk_bf16_f32 v37, v38, v39
	v_cvt_pk_bf16_f32 v38, v32, v33
	v_cvt_pk_bf16_f32 v39, v34, v35
	s_and_b64 vcc, exec, s[38:39]
	global_store_dwordx4 v48, v[36:39], s[24:25] offset:256
	s_cbranch_vccnz .LBB0_704
	v_max_f32_e32 v29, 0, v29
	v_max_f32_e32 v28, 0, v28
	v_max_f32_e32 v31, 0, v31
	v_max_f32_e32 v30, 0, v30
	v_max_f32_e32 v25, 0, v25
	v_max_f32_e32 v24, 0, v24
	v_max_f32_e32 v27, 0, v27
	v_max_f32_e32 v26, 0, v26
	v_pk_mul_f32 v[30:31], v[30:31], v[30:31]
	v_pk_mul_f32 v[28:29], v[28:29], v[28:29]
	v_pk_mul_f32 v[26:27], v[26:27], v[26:27]
	v_pk_mul_f32 v[24:25], v[24:25], v[24:25]
.LBB0_704:
	s_mul_i32 s20, s6, 320
	v_add_u32_e32 v32, s20, v144
	v_cvt_pk_bf16_f32 v28, v28, v29
	v_cvt_pk_bf16_f32 v29, v30, v31
	v_cvt_pk_bf16_f32 v30, v24, v25
	v_cvt_pk_bf16_f32 v31, v26, v27
	s_and_b64 vcc, exec, s[38:39]
	global_store_dwordx4 v32, v[28:31], s[24:25]
	s_cbranch_vccnz .LBB0_706
	v_max_f32_e32 v21, 0, v21
	v_max_f32_e32 v20, 0, v20
	v_max_f32_e32 v23, 0, v23
	v_max_f32_e32 v22, 0, v22
	v_max_f32_e32 v17, 0, v17
	v_max_f32_e32 v16, 0, v16
	v_max_f32_e32 v19, 0, v19
	v_max_f32_e32 v18, 0, v18
	v_pk_mul_f32 v[22:23], v[22:23], v[22:23]
	v_pk_mul_f32 v[20:21], v[20:21], v[20:21]
	v_pk_mul_f32 v[18:19], v[18:19], v[18:19]
	v_pk_mul_f32 v[16:17], v[16:17], v[16:17]
.LBB0_706:
	v_cvt_pk_bf16_f32 v20, v20, v21
	v_cvt_pk_bf16_f32 v21, v22, v23
	v_cvt_pk_bf16_f32 v22, v16, v17
	v_cvt_pk_bf16_f32 v23, v18, v19
	s_and_b64 vcc, exec, s[38:39]
	global_store_dwordx4 v32, v[20:23], s[24:25] offset:256
	s_cbranch_vccnz .LBB0_708
	v_max_f32_e32 v13, 0, v13
	v_max_f32_e32 v12, 0, v12
	v_max_f32_e32 v15, 0, v15
	v_max_f32_e32 v14, 0, v14
	v_max_f32_e32 v9, 0, v9
	v_max_f32_e32 v8, 0, v8
	v_max_f32_e32 v11, 0, v11
	v_max_f32_e32 v10, 0, v10
	v_pk_mul_f32 v[14:15], v[14:15], v[14:15]
	v_pk_mul_f32 v[12:13], v[12:13], v[12:13]
	v_pk_mul_f32 v[10:11], v[10:11], v[10:11]
	v_pk_mul_f32 v[8:9], v[8:9], v[8:9]
.LBB0_708:
	s_mul_i32 s20, s6, 352
	v_add_u32_e32 v16, s20, v144
	v_cvt_pk_bf16_f32 v12, v12, v13
	v_cvt_pk_bf16_f32 v13, v14, v15
	v_cvt_pk_bf16_f32 v14, v8, v9
	v_cvt_pk_bf16_f32 v15, v10, v11
	s_and_b64 vcc, exec, s[38:39]
	global_store_dwordx4 v16, v[12:15], s[24:25]
	s_cbranch_vccnz .LBB0_710
	v_max_f32_e32 v5, 0, v5
	v_max_f32_e32 v4, 0, v4
	v_max_f32_e32 v7, 0, v7
	v_max_f32_e32 v6, 0, v6
	v_max_f32_e32 v1, 0, v1
	v_max_f32_e32 v0, 0, v0
	v_max_f32_e32 v3, 0, v3
	v_max_f32_e32 v2, 0, v2
	v_pk_mul_f32 v[6:7], v[6:7], v[6:7]
	v_pk_mul_f32 v[4:5], v[4:5], v[4:5]
	v_pk_mul_f32 v[2:3], v[2:3], v[2:3]
	v_pk_mul_f32 v[0:1], v[0:1], v[0:1]
.LBB0_710:
	v_cvt_pk_bf16_f32 v4, v4, v5
	v_cvt_pk_bf16_f32 v5, v6, v7
	v_cvt_pk_bf16_f32 v6, v0, v1
	v_cvt_pk_bf16_f32 v7, v2, v3
	s_and_b64 vcc, exec, s[36:37]
	s_mov_b64 s[20:21], -1
	global_store_dwordx4 v16, v[4:7], s[24:25] offset:256
	s_cbranch_vccnz .LBB0_662
	s_andn2_b64 vcc, exec, s[14:15]
	s_cbranch_vccnz .LBB0_661
	s_barrier
	s_branch .LBB0_661
